# neighbourhood tiles: 32 bias LDS reads batched + v_cndmask instead of exec-masked read-wait chains (on v6)
# speedup vs baseline: 1.0181x; 1.0052x over previous
; template <int PM> DI void attn_phase(const Params& p, int l, char* smem, int* s_item, int wv, int cidx) {
;     ...
;             } else {
;               const int kr = tpos >> 6;
;               const int rbase = (kr - qrow + 7) * 31 + (15 - qcol);
; #pragma unroll
;               for (int kb = 0; kb < 2; ++kb)
; #pragma unroll
;                 for (int e = 0; e < 16; ++e) {
;                   const int kidx = kb * 32 + (e & 3) + 8 * (e >> 2) + 4 * h;
;                   const int dc = kidx - cstart;
;                   const bool valid = dc >= 0 && dc < 16;
;                   const float bias = rpb_s[valid ? rbase + kidx : 0];
;                   sacc[kb][e] = valid ? sacc[kb][e] + bias : -1e30f;
;                 }
;             }
.LBB0_441:
	s_and_b64 vcc, exec, s[74:75]
	s_cbranch_vccnz .LBB0_515
	s_andn2_b64 vcc, exec, s[0:1]
	s_cbranch_vccnz .LBB0_512
	s_mov_b64 s[0:1], -1
	s_and_b64 vcc, exec, s[78:79]
	s_cbranch_vccz .LBB0_509
	s_ashr_i32 s0, s92, 6
	s_sub_i32 s0, s0, s82
	s_mul_i32 s0, s0, 31
	v_sub_u32_e32 v0, s0, v205
	s_waitcnt lgkmcnt(2)
	v_lshl_add_u32 v2, v0, 2, v236
	v_lshl_add_u32 v0, v198, 2, v2
	v_lshl_add_u32 v3, v248, 2, v2
	v_lshl_add_u32 v4, v249, 2, v2
	v_lshl_add_u32 v5, v250, 2, v2
	ds_read_b32 v48, v0 offset:928
	ds_read_b32 v49, v0 offset:932
	ds_read_b32 v50, v0 offset:936
	ds_read_b32 v51, v0 offset:940
	ds_read_b32 v52, v0 offset:960
	ds_read_b32 v53, v0 offset:964
	ds_read_b32 v54, v0 offset:968
	ds_read_b32 v55, v0 offset:972
	ds_read_b32 v56, v0 offset:992
	ds_read_b32 v57, v0 offset:996
	ds_read_b32 v58, v0 offset:1000
	ds_read_b32 v59, v0 offset:1004
	ds_read_b32 v60, v0 offset:1024
	ds_read_b32 v61, v0 offset:1028
	ds_read_b32 v62, v0 offset:1032
	ds_read_b32 v63, v0 offset:1036
	ds_read_b32 v64, v0 offset:1056
	ds_read_b32 v65, v3 offset:1056
	ds_read_b32 v66, v4 offset:1056
	ds_read_b32 v67, v5 offset:1056
	ds_read_b32 v68, v0 offset:1088
	ds_read_b32 v69, v0 offset:1092
	ds_read_b32 v70, v0 offset:1096
	ds_read_b32 v71, v0 offset:1100
	ds_read_b32 v72, v0 offset:1120
	ds_read_b32 v73, v0 offset:1124
	ds_read_b32 v74, v0 offset:1128
	ds_read_b32 v75, v0 offset:1132
	ds_read_b32 v76, v0 offset:1152
	ds_read_b32 v77, v0 offset:1156
	ds_read_b32 v78, v0 offset:1160
	ds_read_b32 v79, v0 offset:1164
	s_waitcnt lgkmcnt(0)
	v_add_f32_e32 v48, v16, v48
	v_add_f32_e32 v49, v17, v49
	v_add_f32_e32 v50, v18, v50
	v_add_f32_e32 v51, v19, v51
	v_add_f32_e32 v52, v20, v52
	v_add_f32_e32 v53, v21, v53
	v_add_f32_e32 v54, v22, v54
	v_add_f32_e32 v55, v23, v55
	v_add_f32_e32 v56, v24, v56
	v_add_f32_e32 v57, v25, v57
	v_add_f32_e32 v58, v26, v58
	v_add_f32_e32 v59, v27, v59
	v_add_f32_e32 v60, v28, v60
	v_add_f32_e32 v61, v29, v61
	v_add_f32_e32 v62, v30, v62
	v_add_f32_e32 v63, v31, v63
	v_add_f32_e32 v64, v32, v64
	v_add_f32_e32 v65, v33, v65
	v_add_f32_e32 v66, v34, v66
	v_add_f32_e32 v67, v35, v67
	v_add_f32_e32 v68, v36, v68
	v_add_f32_e32 v69, v37, v69
	v_add_f32_e32 v70, v38, v70
	v_add_f32_e32 v71, v39, v71
	v_add_f32_e32 v72, v40, v72
	v_add_f32_e32 v73, v41, v73
	v_add_f32_e32 v74, v42, v74
	v_add_f32_e32 v75, v43, v75
	v_add_f32_e32 v76, v44, v76
	v_add_f32_e32 v77, v45, v77
	v_add_f32_e32 v78, v46, v78
	v_add_f32_e32 v79, v47, v79
	v_cndmask_b32_e64 v48, v237, v48, s[6:7]
	v_cndmask_b32_e64 v49, v237, v49, s[8:9]
	v_cndmask_b32_e64 v50, v237, v50, s[10:11]
	v_cndmask_b32_e64 v51, v237, v51, s[12:13]
	v_cndmask_b32_e64 v52, v237, v52, s[14:15]
	v_cndmask_b32_e64 v53, v237, v53, s[16:17]
	v_cndmask_b32_e64 v54, v237, v54, s[18:19]
	v_cndmask_b32_e64 v55, v237, v55, s[20:21]
	v_cndmask_b32_e64 v56, v237, v56, s[22:23]
	v_cndmask_b32_e64 v57, v237, v57, s[24:25]
	v_cndmask_b32_e64 v58, v237, v58, s[26:27]
	v_cndmask_b32_e64 v59, v237, v59, s[28:29]
	v_cndmask_b32_e64 v60, v237, v60, s[30:31]
	v_cndmask_b32_e64 v61, v237, v61, s[34:35]
	v_cndmask_b32_e64 v62, v237, v62, s[36:37]
	v_cndmask_b32_e64 v63, v237, v63, s[38:39]
	v_cndmask_b32_e64 v64, v237, v64, s[40:41]
	v_cndmask_b32_e64 v65, v237, v65, s[42:43]
	v_cndmask_b32_e64 v66, v237, v66, s[44:45]
	v_cndmask_b32_e64 v67, v237, v67, s[46:47]
	v_cndmask_b32_e64 v68, v237, v68, s[48:49]
	v_cndmask_b32_e64 v69, v237, v69, s[50:51]
	v_cndmask_b32_e64 v70, v237, v70, s[52:53]
	v_cndmask_b32_e64 v71, v237, v71, s[54:55]
	v_cndmask_b32_e64 v72, v237, v72, s[56:57]
	v_cndmask_b32_e64 v73, v237, v73, s[58:59]
	v_cndmask_b32_e64 v74, v237, v74, s[60:61]
	v_cndmask_b32_e64 v75, v237, v75, s[62:63]
	v_cndmask_b32_e64 v76, v237, v76, s[64:65]
	v_cndmask_b32_e64 v77, v237, v77, s[66:67]
	v_cndmask_b32_e64 v78, v237, v78, s[68:69]
	v_cndmask_b32_e64 v79, v237, v79, s[70:71]
	s_mov_b64 s[0:1], 0
